# v32: v30 + grid-barrier L2 invalidate issued at arrive instead of at wait start (overlaps the prep / G2m main loop of the split barriers); its vmcnt wait unchanged
# speedup vs baseline: 1.0011x; 1.0011x over previous
; DEV int opaque_tid() { int t = threadIdx.x; asm volatile("" : "+v"(t)); return t; }
; DEV void xcd_barrier_arrive(const XcdBarrier& b) {
;     asm volatile("s_waitcnt vmcnt(0)" ::: "memory");
;     __syncthreads();
;     const int tid_ = opaque_tid();
;     if (tid_ == 0) {
;         unsigned* bar = b.bar;
;         __builtin_amdgcn_s_waitcnt(0);
;         unsigned nloc = b.st[0], nx = b.st[1];
;         if (nloc == 0u) { xcd_barrier_complete(bar, b.x, nloc, nx); b.st[0] = nloc; b.st[1] = nx; }
; DEV void xcd_wait_lds(LAS char* lds) {
;     ...
;     if (tid_ == 64) asm volatile("buffer_inv sc1\n\ts_waitcnt vmcnt(0)" ::: "memory");
.LBB0_40:
	s_or_b64 exec, exec, s[4:5]
	s_waitcnt vmcnt(0)
	v_mov_b32_e32 v0, v254
	s_barrier
	s_mov_b64 s[100:101], exec
	v_cmp_eq_u32_e64 s[98:99], 64, v254
	s_mov_b64 exec, s[98:99]
	s_cbranch_execz .Leinv0
	buffer_inv sc1
.Leinv0:
	s_mov_b64 exec, s[100:101]
	s_nop 0
	v_cmp_eq_u32_e32 vcc, 0, v0
	s_and_saveexec_b64 s[0:1], vcc
	s_xor_b64 s[6:7], exec, s[0:1]
	s_cbranch_execz .LBB0_68
	s_add_i32 s0, 0, 0x24ff0
	v_mov_b32_e32 v0, s0
	s_waitcnt vmcnt(0) expcnt(0) lgkmcnt(0)
	ds_read_b32 v4, v0
	s_add_i32 s0, 0, 0x24ff4
	v_mov_b32_e32 v0, s0
	ds_read_b32 v2, v0
	s_waitcnt lgkmcnt(1)
	v_cmp_ne_u32_e32 vcc, 0, v4
	s_cbranch_vccnz .LBB0_55
	s_load_dwordx2 s[0:1], s[96:97], 0x4
	s_add_u32 s8, s90, 0xf77e200
	s_mov_b32 s11, 0
	s_waitcnt lgkmcnt(0)
	v_mov_b32_e32 v2, 0
	s_addc_u32 s9, s91, 0
	s_mul_i32 s2, s0, s93
	s_mul_i32 s2, s2, s1
	s_mov_b32 s14, 0
	s_branch .LBB0_44

; DEV int opaque_tid() { int t = threadIdx.x; asm volatile("" : "+v"(t)); return t; }
; #define LAS __attribute__((address_space(3)))
; DEV void xcd_wait_lds(LAS char* lds) {
;     volatile LAS unsigned* st = (volatile LAS unsigned*)(lds + LDS_BYTES - 16);
;     const int tid_ = opaque_tid();
;     if (tid_ == 64) asm volatile("buffer_inv sc1\n\ts_waitcnt vmcnt(0)" ::: "memory");
.LBB0_178:
	v_mov_b32_e32 v2, v254
	s_waitcnt lgkmcnt(0)
	s_barrier
	s_nop 0
	v_cmp_eq_u32_e32 vcc, 64, v2
	s_and_saveexec_b64 s[0:1], vcc
	s_cbranch_execz .LBB0_180
	s_nop 0
	s_waitcnt vmcnt(0)

; DEV int opaque_tid() { int t = threadIdx.x; asm volatile("" : "+v"(t)); return t; }
; DEV void xcd_barrier_arrive(const XcdBarrier& b) {
;     asm volatile("s_waitcnt vmcnt(0)" ::: "memory");
;     __syncthreads();
;     const int tid_ = opaque_tid();
;     if (tid_ == 0) {
;         unsigned* bar = b.bar;
;         __builtin_amdgcn_s_waitcnt(0);
;         unsigned nloc = b.st[0], nx = b.st[1];
;         if (nloc == 0u) { xcd_barrier_complete(bar, b.x, nloc, nx); b.st[0] = nloc; b.st[1] = nx; }
.LBB0_222:
	s_waitcnt vmcnt(0)
	v_mov_b32_e32 v0, v254
	s_waitcnt vmcnt(0)
	s_barrier
	s_mov_b64 s[100:101], exec
	v_cmp_eq_u32_e64 s[98:99], 64, v254
	s_mov_b64 exec, s[98:99]
	s_cbranch_execz .Leinv1
	buffer_inv sc1
.Leinv1:
	s_mov_b64 exec, s[100:101]
	s_nop 0
	v_cmp_eq_u32_e32 vcc, 0, v0
	s_and_saveexec_b64 s[0:1], vcc
	s_xor_b64 s[6:7], exec, s[0:1]
	s_cbranch_execz .LBB0_250
	s_add_i32 s0, 0, 0x24ff0
	v_mov_b32_e32 v0, s0
	s_waitcnt vmcnt(0) expcnt(0) lgkmcnt(0)
	ds_read_b32 v4, v0
	s_add_i32 s0, 0, 0x24ff4
	v_mov_b32_e32 v0, s0
	ds_read_b32 v2, v0
	s_mov_b32 s9, 0
	s_waitcnt lgkmcnt(1)
	v_cmp_ne_u32_e32 vcc, 0, v4
	s_cbranch_vccnz .LBB0_237
	s_load_dword s2, s[96:97], 0x14
	s_load_dwordx2 s[0:1], s[96:97], 0x4
	s_waitcnt lgkmcnt(0)
	v_mov_b32_e32 v2, 0
	s_mov_b32 s14, 0
	s_lshr_b32 s8, s2, 16
	s_and_b32 s2, s2, 0xffff
	s_cmp_lg_u32 s2, 0
	s_cselect_b64 s[4:5], -1, 0
	s_cmp_lg_u64 s[4:5], 0
	s_addc_u32 s0, s0, 0
	s_cmp_lg_u32 s8, 0
	s_cselect_b64 s[4:5], -1, 0
	s_cmp_lg_u64 s[4:5], 0
	s_mul_i32 s2, s0, s3
	s_addc_u32 s0, s1, 0
	s_add_u32 s10, s90, 0xf77e200
	s_mul_i32 s2, s2, s0
	s_addc_u32 s11, s91, 0
	s_branch .LBB0_226

; DEV int opaque_tid() { int t = threadIdx.x; asm volatile("" : "+v"(t)); return t; }
; #define LAS __attribute__((address_space(3)))
; DEV void xcd_wait_lds(LAS char* lds) {
;     volatile LAS unsigned* st = (volatile LAS unsigned*)(lds + LDS_BYTES - 16);
;     const int tid_ = opaque_tid();
;     if (tid_ == 64) asm volatile("buffer_inv sc1\n\ts_waitcnt vmcnt(0)" ::: "memory");
.LBB0_261:
	v_mov_b32_e32 v2, v254
	s_barrier
	s_nop 0
	v_cmp_eq_u32_e32 vcc, 64, v2
	s_and_saveexec_b64 s[0:1], vcc
	s_cbranch_execz .LBB0_263
	s_nop 0
	s_waitcnt vmcnt(0)

; DEV int opaque_tid() { int t = threadIdx.x; asm volatile("" : "+v"(t)); return t; }
; DEV void xcd_barrier_arrive(const XcdBarrier& b) {
;     asm volatile("s_waitcnt vmcnt(0)" ::: "memory");
;     __syncthreads();
;     const int tid_ = opaque_tid();
;     if (tid_ == 0) {
;         unsigned* bar = b.bar;
;         __builtin_amdgcn_s_waitcnt(0);
;         unsigned nloc = b.st[0], nx = b.st[1];
;         if (nloc == 0u) { xcd_barrier_complete(bar, b.x, nloc, nx); b.st[0] = nloc; b.st[1] = nx; }
.LBB0_378:
	s_waitcnt vmcnt(0)
	v_mov_b32_e32 v0, v254
	s_barrier
	s_mov_b64 s[100:101], exec
	v_cmp_eq_u32_e64 s[98:99], 64, v254
	s_mov_b64 exec, s[98:99]
	s_cbranch_execz .Leinv2
	buffer_inv sc1
.Leinv2:
	s_mov_b64 exec, s[100:101]
	s_nop 0
	v_cmp_eq_u32_e32 vcc, 0, v0
	s_and_saveexec_b64 s[0:1], vcc
	s_xor_b64 s[8:9], exec, s[0:1]
	s_cbranch_execz .LBB0_406
	s_add_i32 s0, 0, 0x24ff0
	v_mov_b32_e32 v0, s0
	s_waitcnt vmcnt(0) expcnt(0) lgkmcnt(0)
	ds_read_b32 v4, v0
	s_add_i32 s0, 0, 0x24ff4
	v_mov_b32_e32 v0, s0
	ds_read_b32 v2, v0
	s_waitcnt lgkmcnt(1)
	v_cmp_ne_u32_e32 vcc, 0, v4
	s_cbranch_vccnz .LBB0_393
	s_load_dword s2, s[96:97], 0x14
	s_load_dwordx2 s[0:1], s[96:97], 0x4
	s_mov_b32 s13, 0
	s_waitcnt lgkmcnt(0)
	v_mov_b32_e32 v2, 0
	s_mov_b32 s16, 0
	s_lshr_b32 s6, s2, 16
	s_and_b32 s2, s2, 0xffff
	s_cmp_lg_u32 s2, 0
	s_cselect_b64 s[4:5], -1, 0
	s_cmp_lg_u64 s[4:5], 0
	s_addc_u32 s0, s0, 0
	s_cmp_lg_u32 s6, 0
	s_cselect_b64 s[4:5], -1, 0
	s_cmp_lg_u64 s[4:5], 0
	s_mul_i32 s2, s0, s3
	s_addc_u32 s0, s1, 0
	s_add_u32 s10, s90, 0xf77e200
	s_mul_i32 s2, s2, s0
	s_addc_u32 s11, s91, 0
	s_branch .LBB0_382

; DEV int opaque_tid() { int t = threadIdx.x; asm volatile("" : "+v"(t)); return t; }
; #define LAS __attribute__((address_space(3)))
; DEV void xcd_wait_lds(LAS char* lds) {
;     volatile LAS unsigned* st = (volatile LAS unsigned*)(lds + LDS_BYTES - 16);
;     const int tid_ = opaque_tid();
;     if (tid_ == 64) asm volatile("buffer_inv sc1\n\ts_waitcnt vmcnt(0)" ::: "memory");
.LBB0_428:
	s_or_b64 exec, exec, s[4:5]
	v_mov_b32_e32 v2, v254
	s_barrier
	s_nop 0
	v_cmp_eq_u32_e32 vcc, 64, v2
	s_and_saveexec_b64 s[0:1], vcc
	s_cbranch_execz .LBB0_430
	s_nop 0
	s_waitcnt vmcnt(0)

; DEV int opaque_tid() { int t = threadIdx.x; asm volatile("" : "+v"(t)); return t; }
; DEV void xcd_barrier_arrive(const XcdBarrier& b) {
;     ...
;     const int tid_ = opaque_tid();
;     if (tid_ == 0) {
;         unsigned* bar = b.bar;
;         __builtin_amdgcn_s_waitcnt(0);
;         unsigned nloc = b.st[0], nx = b.st[1];
;         if (nloc == 0u) { xcd_barrier_complete(bar, b.x, nloc, nx); b.st[0] = nloc; b.st[1] = nx; }
.Leinv3:
	s_mov_b64 exec, s[100:101]
	s_nop 0
	v_cmp_eq_u32_e32 vcc, 0, v0
	s_and_saveexec_b64 s[0:1], vcc
	s_xor_b64 s[8:9], exec, s[0:1]
	s_cbranch_execz .LBB0_560
	s_add_i32 s0, 0, 0x24ff0
	v_mov_b32_e32 v0, s0
	s_waitcnt vmcnt(0) expcnt(0) lgkmcnt(0)
	ds_read_b32 v4, v0
	s_add_i32 s0, 0, 0x24ff4
	v_mov_b32_e32 v0, s0
	ds_read_b32 v2, v0
	s_mov_b32 s11, 0
	s_waitcnt lgkmcnt(1)
	v_cmp_ne_u32_e32 vcc, 0, v4
	s_cbranch_vccnz .LBB0_547
	s_load_dword s2, s[96:97], 0x14
	s_load_dwordx2 s[0:1], s[96:97], 0x4
	s_waitcnt lgkmcnt(0)
	v_mov_b32_e32 v2, 0
	s_mov_b32 s16, 0
	s_lshr_b32 s6, s2, 16
	s_and_b32 s2, s2, 0xffff
	s_cmp_lg_u32 s2, 0
	s_cselect_b64 s[4:5], -1, 0
	s_cmp_lg_u64 s[4:5], 0
	s_addc_u32 s0, s0, 0
	s_cmp_lg_u32 s6, 0
	s_cselect_b64 s[4:5], -1, 0
	s_cmp_lg_u64 s[4:5], 0
	s_mul_i32 s2, s0, s3
	s_addc_u32 s0, s1, 0
	s_add_u32 s12, s90, 0xf77e200
	s_mul_i32 s2, s2, s0
	s_addc_u32 s13, s91, 0
	s_branch .LBB0_536

; DEV int opaque_tid() { int t = threadIdx.x; asm volatile("" : "+v"(t)); return t; }
; #define LAS __attribute__((address_space(3)))
; DEV void xcd_wait_lds(LAS char* lds) {
;     volatile LAS unsigned* st = (volatile LAS unsigned*)(lds + LDS_BYTES - 16);
;     const int tid_ = opaque_tid();
;     if (tid_ == 64) asm volatile("buffer_inv sc1\n\ts_waitcnt vmcnt(0)" ::: "memory");
.LBB0_567:
	s_waitcnt lgkmcnt(2)
	v_mov_b32_e32 v2, v254
	s_nop 0
	v_cmp_eq_u32_e32 vcc, 64, v2
	s_and_saveexec_b64 s[0:1], vcc
	s_cbranch_execz .LBB0_569
	s_nop 0
	s_waitcnt vmcnt(0)

; DEV int opaque_tid() { int t = threadIdx.x; asm volatile("" : "+v"(t)); return t; }
; DEV void xcd_barrier_arrive(const XcdBarrier& b) {
;     asm volatile("s_waitcnt vmcnt(0)" ::: "memory");
;     __syncthreads();
;     const int tid_ = opaque_tid();
; DEV void xcd_wait_lds(LAS char* lds) {
;     ...
;     if (tid_ == 64) asm volatile("buffer_inv sc1\n\ts_waitcnt vmcnt(0)" ::: "memory");
.LBB0_677:
	s_waitcnt vmcnt(0)
	v_mov_b32_e32 v0, v254
	s_waitcnt lgkmcnt(0)
	s_barrier
	s_mov_b64 s[100:101], exec
	v_cmp_eq_u32_e64 s[98:99], 64, v254
	s_mov_b64 exec, s[98:99]
	s_cbranch_execz .Leinv4
	buffer_inv sc1

; DEV int opaque_tid() { int t = threadIdx.x; asm volatile("" : "+v"(t)); return t; }
; #define LAS __attribute__((address_space(3)))
; DEV void xcd_wait_lds(LAS char* lds) {
;     volatile LAS unsigned* st = (volatile LAS unsigned*)(lds + LDS_BYTES - 16);
;     const int tid_ = opaque_tid();
;     if (tid_ == 64) asm volatile("buffer_inv sc1\n\ts_waitcnt vmcnt(0)" ::: "memory");
.LBB0_717:
	v_mov_b32_e32 v214, v202
	v_mov_b32_e32 v130, v203
	v_mov_b32_e32 v0, s68
	ds_read_b32 v0, v0
	s_waitcnt lgkmcnt(0)
	v_readfirstlane_b32 s0, v0
	s_cmp_eq_u32 s0, 0
	s_cbranch_scc1 .LBB0_743
	v_mov_b32_e32 v131, v254
	s_nop 0
	v_cmp_eq_u32_e32 vcc, 64, v131
	s_and_saveexec_b64 s[0:1], vcc
	s_cbranch_execz .LBB0_720
	s_nop 0
	s_waitcnt vmcnt(0)

; DEV int opaque_tid() { int t = threadIdx.x; asm volatile("" : "+v"(t)); return t; }
; DEV void xcd_barrier_arrive(const XcdBarrier& b) {
;     ...
;     const int tid_ = opaque_tid();
;     if (tid_ == 0) {
;         unsigned* bar = b.bar;
;         __builtin_amdgcn_s_waitcnt(0);
;         unsigned nloc = b.st[0], nx = b.st[1];
;         if (nloc == 0u) { xcd_barrier_complete(bar, b.x, nloc, nx); b.st[0] = nloc; b.st[1] = nx; }
.Leinv5:
	s_mov_b64 exec, s[100:101]
	s_nop 0
	v_cmp_eq_u32_e32 vcc, 0, v0
	s_and_saveexec_b64 s[8:9], vcc
	s_cbranch_execz .LBB0_809
	s_add_i32 s0, 0, 0x24ff0
	v_mov_b32_e32 v0, s0
	s_waitcnt vmcnt(0) expcnt(0) lgkmcnt(0)
	ds_read_b32 v4, v0
	s_add_i32 s0, 0, 0x24ff4
	v_mov_b32_e32 v0, s0
	ds_read_b32 v2, v0
	s_mov_b32 s11, 0
	s_waitcnt lgkmcnt(1)
	v_cmp_ne_u32_e32 vcc, 0, v4
	s_cbranch_vccnz .LBB0_796
	s_load_dword s2, s[96:97], 0x14
	s_load_dwordx2 s[0:1], s[96:97], 0x4
	s_waitcnt lgkmcnt(0)
	v_mov_b32_e32 v2, 0
	s_mov_b32 s16, 0
	s_lshr_b32 s6, s2, 16
	s_and_b32 s2, s2, 0xffff
	s_cmp_lg_u32 s2, 0
	s_cselect_b64 s[4:5], -1, 0
	s_cmp_lg_u64 s[4:5], 0
	s_addc_u32 s0, s0, 0
	s_cmp_lg_u32 s6, 0
	s_cselect_b64 s[4:5], -1, 0
	s_cmp_lg_u64 s[4:5], 0
	s_mul_i32 s2, s0, s3
	s_addc_u32 s0, s1, 0
	s_add_u32 s12, s90, 0xf77e200
	s_mul_i32 s2, s2, s0
	s_addc_u32 s13, s91, 0
	s_branch .LBB0_785

; DEV int opaque_tid() { int t = threadIdx.x; asm volatile("" : "+v"(t)); return t; }
; #define LAS __attribute__((address_space(3)))
; DEV void xcd_wait_lds(LAS char* lds) {
;     volatile LAS unsigned* st = (volatile LAS unsigned*)(lds + LDS_BYTES - 16);
;     const int tid_ = opaque_tid();
;     if (tid_ == 64) asm volatile("buffer_inv sc1\n\ts_waitcnt vmcnt(0)" ::: "memory");
.LBB0_818:
	s_or_b64 exec, exec, s[22:23]
	v_mov_b32_e32 v2, v254
	s_waitcnt lgkmcnt(0)
	s_barrier
	s_nop 0
	v_cmp_eq_u32_e32 vcc, 64, v2
	s_and_saveexec_b64 s[0:1], vcc
	s_cbranch_execz .LBB0_820
	s_nop 0
	s_waitcnt vmcnt(0)

; DEV int opaque_tid() { int t = threadIdx.x; asm volatile("" : "+v"(t)); return t; }
; DEV void xcd_barrier_arrive(const XcdBarrier& b) {
;     asm volatile("s_waitcnt vmcnt(0)" ::: "memory");
;     __syncthreads();
;     const int tid_ = opaque_tid();
;     if (tid_ == 0) {
;         unsigned* bar = b.bar;
;         __builtin_amdgcn_s_waitcnt(0);
;         unsigned nloc = b.st[0], nx = b.st[1];
;         if (nloc == 0u) { xcd_barrier_complete(bar, b.x, nloc, nx); b.st[0] = nloc; b.st[1] = nx; }
.LBB0_904:
	s_barrier
	s_waitcnt vmcnt(0)
	v_mov_b32_e32 v0, v254
	s_barrier
	s_mov_b64 s[100:101], exec
	v_cmp_eq_u32_e64 s[98:99], 64, v254
	s_mov_b64 exec, s[98:99]
	s_cbranch_execz .Leinv6
	buffer_inv sc1
.Leinv6:
	s_mov_b64 exec, s[100:101]
	s_nop 0
	v_cmp_eq_u32_e32 vcc, 0, v0
	s_and_saveexec_b64 s[8:9], vcc
	s_cbranch_execz .LBB0_932
	s_add_i32 s0, 0, 0x24ff0
	v_mov_b32_e32 v0, s0
	s_waitcnt vmcnt(0) expcnt(0) lgkmcnt(0)
	ds_read_b32 v4, v0
	s_add_i32 s0, 0, 0x24ff4
	v_mov_b32_e32 v0, s0
	ds_read_b32 v2, v0
	s_waitcnt lgkmcnt(1)
	v_cmp_ne_u32_e32 vcc, 0, v4
	s_cbranch_vccnz .LBB0_919
	s_load_dwordx2 s[0:1], s[96:97], 0x4
	s_add_u32 s10, s90, 0xf77e200
	s_mov_b32 s13, 0
	s_waitcnt lgkmcnt(0)
	v_mov_b32_e32 v2, 0
	s_addc_u32 s11, s91, 0
	s_mul_i32 s2, s0, s3
	s_mul_i32 s2, s2, s1
	s_mov_b32 s16, 0
	s_branch .LBB0_908

; DEV int opaque_tid() { int t = threadIdx.x; asm volatile("" : "+v"(t)); return t; }
; DEV void xcd_barrier_arrive(const XcdBarrier& b) {
;     ...
;     const int tid_ = opaque_tid();
;     if (tid_ == 0) {
;         unsigned* bar = b.bar;
;         __builtin_amdgcn_s_waitcnt(0);
;         unsigned nloc = b.st[0], nx = b.st[1];
;         if (nloc == 0u) { xcd_barrier_complete(bar, b.x, nloc, nx); b.st[0] = nloc; b.st[1] = nx; }
.Leinv10:
	s_mov_b64 exec, s[100:101]
	s_nop 0
	v_cmp_eq_u32_e32 vcc, 0, v0
	s_and_saveexec_b64 s[0:1], vcc
	s_xor_b64 s[8:9], exec, s[0:1]
	v_readlane_b32 s68, v255, 9
	v_readlane_b32 s70, v255, 7
	v_readlane_b32 s69, v255, 10
	v_readlane_b32 s71, v255, 8
	s_cbranch_execz .LBB0_1556
	s_add_i32 s0, 0, 0x24ff0
	v_mov_b32_e32 v0, s0
	s_waitcnt vmcnt(0) expcnt(0) lgkmcnt(0)
	ds_read_b32 v4, v0
	s_add_i32 s0, 0, 0x24ff4
	v_mov_b32_e32 v0, s0
	ds_read_b32 v2, v0
	s_mov_b32 s11, 0
	s_waitcnt lgkmcnt(1)
	v_cmp_ne_u32_e32 vcc, 0, v4
	s_cbranch_vccnz .LBB0_1543
	s_load_dword s2, s[96:97], 0x14
	s_load_dwordx2 s[0:1], s[96:97], 0x4
	s_waitcnt lgkmcnt(0)
	v_mov_b32_e32 v2, 0
	s_mov_b32 s16, 0
	s_lshr_b32 s6, s2, 16
	s_and_b32 s2, s2, 0xffff
	s_cmp_lg_u32 s2, 0
	s_cselect_b64 s[4:5], -1, 0
	s_cmp_lg_u64 s[4:5], 0
	s_addc_u32 s0, s0, 0
	s_cmp_lg_u32 s6, 0
	s_cselect_b64 s[4:5], -1, 0
	s_cmp_lg_u64 s[4:5], 0
	s_mul_i32 s2, s0, s3
	s_addc_u32 s0, s1, 0
	s_add_u32 s12, s90, 0xf77e200
	s_mul_i32 s2, s2, s0
	s_addc_u32 s13, s91, 0
	s_branch .LBB0_1532

; DEV int opaque_tid() { int t = threadIdx.x; asm volatile("" : "+v"(t)); return t; }
; #define LAS __attribute__((address_space(3)))
; DEV void xcd_wait_lds(LAS char* lds) {
;     volatile LAS unsigned* st = (volatile LAS unsigned*)(lds + LDS_BYTES - 16);
;     const int tid_ = opaque_tid();
;     if (tid_ == 64) asm volatile("buffer_inv sc1\n\ts_waitcnt vmcnt(0)" ::: "memory");
.LBB0_1568:
	v_mov_b32_e32 v214, v202
	v_mov_b32_e32 v148, v203
	v_mov_b32_e32 v0, s82
	ds_read_b32 v0, v0
	s_waitcnt lgkmcnt(0)
	v_readfirstlane_b32 s6, v0
	s_cmp_eq_u32 s6, 0
	s_cbranch_scc1 .LBB0_1594
	v_mov_b32_e32 v142, v254
	s_nop 0
	v_cmp_eq_u32_e32 vcc, 64, v142
	s_and_saveexec_b64 s[6:7], vcc
	s_cbranch_execz .LBB0_1571
	s_nop 0
	s_waitcnt vmcnt(0)

; DEV int opaque_tid() { int t = threadIdx.x; asm volatile("" : "+v"(t)); return t; }
; DEV void xcd_barrier1(const XcdBarrier& b) {
;     asm volatile("s_waitcnt vmcnt(0)" ::: "memory");
;     __syncthreads();
;     const int tid_ = opaque_tid();
;     if (tid_ == 64) asm volatile("buffer_inv sc1\n\ts_waitcnt vmcnt(0)" ::: "memory");
;     if (tid_ == 0) {
;         unsigned* bar = b.bar;
;         __builtin_amdgcn_s_waitcnt(0);
;         unsigned nloc = b.st[0], nx = b.st[1];
.LBB0_1632:
	s_waitcnt vmcnt(0)
	v_mov_b32_e32 v2, v254
	s_barrier
	s_mov_b64 s[100:101], exec
	v_cmp_eq_u32_e64 s[98:99], 64, v254
	s_mov_b64 exec, s[98:99]
	s_cbranch_execz .Leinv11
	buffer_inv sc1
.Leinv11:
	s_mov_b64 exec, s[100:101]
	s_nop 0
	v_cmp_lt_i32_e32 vcc, 63, v2
	s_and_saveexec_b64 s[0:1], vcc
	s_xor_b64 s[0:1], exec, s[0:1]
	s_cbranch_execz .LBB0_1636
	v_cmp_eq_u32_e32 vcc, 64, v2
	s_and_saveexec_b64 s[4:5], vcc
	s_cbranch_execz .LBB0_1635
	s_nop 0
	s_waitcnt vmcnt(0)
